# G2/G4 residual epilogue regenerated: all 16 residual loads prefetched, counted vmcnt(14), bpermute hops batched across 8 rows, single masked part-store block; bit-identical
# baseline (speedup 1.0000x reference)
; __device__ __forceinline__ unsigned cvt_pk_bf16(float lo, float hi) { unsigned r; asm volatile("v_cvt_pk_bf16_f32 %0, %1, %2" : "=v"(r) : "v"(lo), "v"(hi)); return r; }
; __device__ __forceinline__ float bf_lo(unsigned w) { return __uint_as_float(w << 16); }
; __device__ __forceinline__ float bf_hi(unsigned w) { return __uint_as_float(w & 0xffff0000u); }
;     __device__ __forceinline__ void operator()(const f32x4 (&acc)[2][2][4][2], const Unit& u, int wr, int wc, int fr, int fq) const {
;         const int row0 = u.pm * BM + wr * 64 + fr, col0 = u.pn * BM + wc * 32 + 8 * fq;
; #pragma unroll
;         for (int ai = 0; ai < 2; ++ai) {
;             u32x4 xr[4][2];
; #pragma unroll
;             for (int m = 0; m < 4; ++m)
; #pragma unroll
;                 for (int bj = 0; bj < 2; ++bj) xr[m][bj] = *(const u32x4*)(xb + (size_t)(row0 + ai * HALF + m * 16) * ldc + col0 + bj * HALF);
;             asm volatile("" : "+v"(xr[0][0]), "+v"(xr[0][1]), "+v"(xr[1][0]), "+v"(xr[1][1]), "+v"(xr[2][0]), "+v"(xr[2][1]), "+v"(xr[3][0]), "+v"(xr[3][1]));
; #pragma unroll
;             for (int m = 0; m < 4; ++m) { const int row = row0 + ai * HALF + m * 16; const size_t off = (size_t)row * ldc + col0; float s = 0.f;
; #pragma unroll
;                 for (int bj = 0; bj < 2; ++bj) { const u32x4 b = xr[m][bj];
;                     const f32x4 v0 = (f32x4){bf_lo(b.x), bf_hi(b.x), bf_lo(b.y), bf_hi(b.y)} + acc[ai][bj][m][0], v1 = (f32x4){bf_lo(b.z), bf_hi(b.z), bf_lo(b.w), bf_hi(b.w)} + acc[ai][bj][m][1];
;                     u32x4 w; w.x = cvt_pk_bf16(v0[0], v0[1]); w.y = cvt_pk_bf16(v0[2], v0[3]); w.z = cvt_pk_bf16(v1[0], v1[1]); w.w = cvt_pk_bf16(v1[2], v1[3]); *(u32x4*)(xb + off + bj * HALF) = w;
;                     s += (v0[0] * v0[0] + v0[1] * v0[1]) + (v0[2] * v0[2] + v0[3] * v0[3]) + (v1[0] * v1[0] + v1[1] * v1[1]) + (v1[2] * v1[2] + v1[3] * v1[3]); }
;                 s += __shfl_xor(s, 16); s += __shfl_xor(s, 32); if (fq == 0) part[((size_t)u.pm * 32 + u.pn * 4 + wc) * 256 + (row & 255)] = s; }
.LBB0_319:
	v_lshl_or_b32 v197, s75, 8, v212
	v_lshl_add_u32 v196, s94, 8, v210
	v_lshlrev_b32_e32 v196, 12, v196
	v_lshl_add_u32 v196, v197, 1, v196
	v_mov_b32_e32 v197, v196
	global_load_dwordx4 v[128:131], v197, s[64:65]
	global_load_dwordx4 v[132:135], v197, s[64:65] offset:256
	v_add_u32_e32 v197, 0x10000, v196
	global_load_dwordx4 v[136:139], v197, s[64:65]
	global_load_dwordx4 v[140:143], v197, s[64:65] offset:256
	v_add_u32_e32 v197, 0x20000, v196
	global_load_dwordx4 v[144:147], v197, s[64:65]
	global_load_dwordx4 v[148:151], v197, s[64:65] offset:256
	v_add_u32_e32 v197, 0x30000, v196
	global_load_dwordx4 v[178:181], v197, s[64:65]
	global_load_dwordx4 v[182:185], v197, s[64:65] offset:256
	v_add_u32_e32 v197, 0x80000, v196
	global_load_dwordx4 v[186:189], v197, s[64:65]
	global_load_dwordx4 v[214:217], v197, s[64:65] offset:256
	v_add_u32_e32 v197, 0x90000, v196
	global_load_dwordx4 v[218:221], v197, s[64:65]
	global_load_dwordx4 v[222:225], v197, s[64:65] offset:256
	v_add_u32_e32 v197, 0xa0000, v196
	global_load_dwordx4 v[226:229], v197, s[64:65]
	global_load_dwordx4 v[230:233], v197, s[64:65] offset:256
	v_add_u32_e32 v197, 0xb0000, v196
	global_load_dwordx4 v[234:237], v197, s[64:65]
	global_load_dwordx4 v[238:241], v197, s[64:65] offset:256
	s_ashr_i32 s95, s94, 31
	s_lshl_b32 s46, s75, 2
	s_lshl_b64 s[28:29], s[94:95], 5
	s_ashr_i32 s47, s46, 31
	s_add_u32 s28, s28, s46
	s_addc_u32 s29, s29, s47
	s_or_b64 s[28:29], s[28:29], s[82:83]
	s_lshl_b64 s[94:95], s[28:29], 10
	s_waitcnt vmcnt(14)
	v_mov_b32_e32 v197, v196
	v_lshlrev_b32_e32 v242, 16, v128
	v_and_b32_e32 v243, 0xffff0000, v128
	v_lshlrev_b32_e32 v244, 16, v129
	v_and_b32_e32 v245, 0xffff0000, v129
	v_lshlrev_b32_e32 v246, 16, v130
	v_and_b32_e32 v247, 0xffff0000, v130
	v_lshlrev_b32_e32 v198, 16, v131
	v_and_b32_e32 v199, 0xffff0000, v131
	v_pk_add_f32 v[126:127], v[126:127], v[244:245]
	v_pk_add_f32 v[124:125], v[124:125], v[242:243]
	v_pk_add_f32 v[120:121], v[120:121], v[246:247]
	v_pk_add_f32 v[122:123], v[122:123], v[198:199]
	v_cvt_pk_bf16_f32 v242, v124, v125
	v_cvt_pk_bf16_f32 v243, v126, v127
	v_cvt_pk_bf16_f32 v244, v120, v121
	v_cvt_pk_bf16_f32 v245, v122, v123
	global_store_dwordx4 v197, v[242:245], s[64:65]
	v_mul_f32_e32 v246, v125, v125
	v_mul_f32_e32 v247, v127, v127
	v_fmac_f32_e32 v246, v124, v124
	v_fmac_f32_e32 v247, v126, v126
	v_add_f32_e32 v246, v246, v247
	v_mul_f32_e32 v247, v121, v121
	v_fmac_f32_e32 v247, v120, v120
	v_add_f32_e32 v246, v247, v246
	v_mul_f32_e32 v247, v123, v123
	v_fmac_f32_e32 v247, v122, v122
	v_add_f32_e32 v128, v247, v246
	v_lshlrev_b32_e32 v242, 16, v132
	v_and_b32_e32 v243, 0xffff0000, v132
	v_lshlrev_b32_e32 v244, 16, v133
	v_and_b32_e32 v245, 0xffff0000, v133
	v_lshlrev_b32_e32 v246, 16, v134
	v_and_b32_e32 v247, 0xffff0000, v134
	v_lshlrev_b32_e32 v198, 16, v135
	v_and_b32_e32 v199, 0xffff0000, v135
	v_pk_add_f32 v[118:119], v[118:119], v[244:245]
	v_pk_add_f32 v[116:117], v[116:117], v[242:243]
	v_pk_add_f32 v[112:113], v[112:113], v[246:247]
	v_pk_add_f32 v[114:115], v[114:115], v[198:199]
	v_cvt_pk_bf16_f32 v242, v116, v117
	v_cvt_pk_bf16_f32 v243, v118, v119
	v_cvt_pk_bf16_f32 v244, v112, v113
	v_cvt_pk_bf16_f32 v245, v114, v115
	global_store_dwordx4 v197, v[242:245], s[64:65] offset:256
	v_mul_f32_e32 v246, v117, v117
	v_mul_f32_e32 v247, v119, v119
	v_fmac_f32_e32 v246, v116, v116
	v_fmac_f32_e32 v247, v118, v118
	v_add_f32_e32 v246, v246, v247
	v_mul_f32_e32 v247, v113, v113
	v_fmac_f32_e32 v247, v112, v112
	v_add_f32_e32 v246, v247, v246
	v_mul_f32_e32 v247, v115, v115
	v_fmac_f32_e32 v247, v114, v114
	v_add_f32_e32 v246, v247, v246
	v_add_f32_e32 v128, v128, v246
	s_waitcnt vmcnt(14)
	v_add_u32_e32 v197, 0x10000, v196
	v_lshlrev_b32_e32 v242, 16, v136
	v_and_b32_e32 v243, 0xffff0000, v136
	v_lshlrev_b32_e32 v244, 16, v137
	v_and_b32_e32 v245, 0xffff0000, v137
	v_lshlrev_b32_e32 v246, 16, v138
	v_and_b32_e32 v247, 0xffff0000, v138
	v_lshlrev_b32_e32 v198, 16, v139
	v_and_b32_e32 v199, 0xffff0000, v139
	v_pk_add_f32 v[110:111], v[110:111], v[244:245]
	v_pk_add_f32 v[108:109], v[108:109], v[242:243]
	v_pk_add_f32 v[104:105], v[104:105], v[246:247]
	v_pk_add_f32 v[106:107], v[106:107], v[198:199]
	v_cvt_pk_bf16_f32 v242, v108, v109
	v_cvt_pk_bf16_f32 v243, v110, v111
	v_cvt_pk_bf16_f32 v244, v104, v105
	v_cvt_pk_bf16_f32 v245, v106, v107
	global_store_dwordx4 v197, v[242:245], s[64:65]
	v_mul_f32_e32 v246, v109, v109
	v_mul_f32_e32 v247, v111, v111
	v_fmac_f32_e32 v246, v108, v108
	v_fmac_f32_e32 v247, v110, v110
	v_add_f32_e32 v246, v246, v247
	v_mul_f32_e32 v247, v105, v105
	v_fmac_f32_e32 v247, v104, v104
	v_add_f32_e32 v246, v247, v246
	v_mul_f32_e32 v247, v107, v107
	v_fmac_f32_e32 v247, v106, v106
	v_add_f32_e32 v136, v247, v246
	v_lshlrev_b32_e32 v242, 16, v140
	v_and_b32_e32 v243, 0xffff0000, v140
	v_lshlrev_b32_e32 v244, 16, v141
	v_and_b32_e32 v245, 0xffff0000, v141
	v_lshlrev_b32_e32 v246, 16, v142
	v_and_b32_e32 v247, 0xffff0000, v142
	v_lshlrev_b32_e32 v198, 16, v143
	v_and_b32_e32 v199, 0xffff0000, v143
	v_pk_add_f32 v[102:103], v[102:103], v[244:245]
	v_pk_add_f32 v[100:101], v[100:101], v[242:243]
	v_pk_add_f32 v[96:97], v[96:97], v[246:247]
	v_pk_add_f32 v[98:99], v[98:99], v[198:199]
	v_cvt_pk_bf16_f32 v242, v100, v101
	v_cvt_pk_bf16_f32 v243, v102, v103
	v_cvt_pk_bf16_f32 v244, v96, v97
	v_cvt_pk_bf16_f32 v245, v98, v99
	global_store_dwordx4 v197, v[242:245], s[64:65] offset:256
	v_mul_f32_e32 v246, v101, v101
	v_mul_f32_e32 v247, v103, v103
	v_fmac_f32_e32 v246, v100, v100
	v_fmac_f32_e32 v247, v102, v102
	v_add_f32_e32 v246, v246, v247
	v_mul_f32_e32 v247, v97, v97
	v_fmac_f32_e32 v247, v96, v96
	v_add_f32_e32 v246, v247, v246
	v_mul_f32_e32 v247, v99, v99
	v_fmac_f32_e32 v247, v98, v98
	v_add_f32_e32 v246, v247, v246
	v_add_f32_e32 v136, v136, v246
	s_waitcnt vmcnt(14)
; __device__ __forceinline__ unsigned cvt_pk_bf16(float lo, float hi) { unsigned r; asm volatile("v_cvt_pk_bf16_f32 %0, %1, %2" : "=v"(r) : "v"(lo), "v"(hi)); return r; }
; __device__ __forceinline__ float bf_lo(unsigned w) { return __uint_as_float(w << 16); }
; __device__ __forceinline__ float bf_hi(unsigned w) { return __uint_as_float(w & 0xffff0000u); }
;     __device__ __forceinline__ void operator()(const f32x4 (&acc)[2][2][4][2], const Unit& u, int wr, int wc, int fr, int fq) const {
;         const int row0 = u.pm * BM + wr * 64 + fr, col0 = u.pn * BM + wc * 32 + 8 * fq;
; #pragma unroll
;         for (int ai = 0; ai < 2; ++ai) {
;             u32x4 xr[4][2];
; #pragma unroll
;             for (int m = 0; m < 4; ++m)
; #pragma unroll
;                 for (int bj = 0; bj < 2; ++bj) xr[m][bj] = *(const u32x4*)(xb + (size_t)(row0 + ai * HALF + m * 16) * ldc + col0 + bj * HALF);
;             asm volatile("" : "+v"(xr[0][0]), "+v"(xr[0][1]), "+v"(xr[1][0]), "+v"(xr[1][1]), "+v"(xr[2][0]), "+v"(xr[2][1]), "+v"(xr[3][0]), "+v"(xr[3][1]));
; #pragma unroll
;             for (int m = 0; m < 4; ++m) { const int row = row0 + ai * HALF + m * 16; const size_t off = (size_t)row * ldc + col0; float s = 0.f;
; #pragma unroll
;                 for (int bj = 0; bj < 2; ++bj) { const u32x4 b = xr[m][bj];
;                     const f32x4 v0 = (f32x4){bf_lo(b.x), bf_hi(b.x), bf_lo(b.y), bf_hi(b.y)} + acc[ai][bj][m][0], v1 = (f32x4){bf_lo(b.z), bf_hi(b.z), bf_lo(b.w), bf_hi(b.w)} + acc[ai][bj][m][1];
;                     u32x4 w; w.x = cvt_pk_bf16(v0[0], v0[1]); w.y = cvt_pk_bf16(v0[2], v0[3]); w.z = cvt_pk_bf16(v1[0], v1[1]); w.w = cvt_pk_bf16(v1[2], v1[3]); *(u32x4*)(xb + off + bj * HALF) = w;
;                     s += (v0[0] * v0[0] + v0[1] * v0[1]) + (v0[2] * v0[2] + v0[3] * v0[3]) + (v1[0] * v1[0] + v1[1] * v1[1]) + (v1[2] * v1[2] + v1[3] * v1[3]); }
;                 s += __shfl_xor(s, 16); s += __shfl_xor(s, 32); if (fq == 0) part[((size_t)u.pm * 32 + u.pn * 4 + wc) * 256 + (row & 255)] = s; }
	v_add_u32_e32 v197, 0x20000, v196
	v_lshlrev_b32_e32 v242, 16, v144
	v_and_b32_e32 v243, 0xffff0000, v144
	v_lshlrev_b32_e32 v244, 16, v145
	v_and_b32_e32 v245, 0xffff0000, v145
	v_lshlrev_b32_e32 v246, 16, v146
	v_and_b32_e32 v247, 0xffff0000, v146
	v_lshlrev_b32_e32 v198, 16, v147
	v_and_b32_e32 v199, 0xffff0000, v147
	v_pk_add_f32 v[94:95], v[94:95], v[244:245]
	v_pk_add_f32 v[92:93], v[92:93], v[242:243]
	v_pk_add_f32 v[88:89], v[88:89], v[246:247]
	v_pk_add_f32 v[90:91], v[90:91], v[198:199]
	v_cvt_pk_bf16_f32 v242, v92, v93
	v_cvt_pk_bf16_f32 v243, v94, v95
	v_cvt_pk_bf16_f32 v244, v88, v89
	v_cvt_pk_bf16_f32 v245, v90, v91
	global_store_dwordx4 v197, v[242:245], s[64:65]
	v_mul_f32_e32 v246, v93, v93
	v_mul_f32_e32 v247, v95, v95
	v_fmac_f32_e32 v246, v92, v92
	v_fmac_f32_e32 v247, v94, v94
	v_add_f32_e32 v246, v246, v247
	v_mul_f32_e32 v247, v89, v89
	v_fmac_f32_e32 v247, v88, v88
	v_add_f32_e32 v246, v247, v246
	v_mul_f32_e32 v247, v91, v91
	v_fmac_f32_e32 v247, v90, v90
	v_add_f32_e32 v144, v247, v246
	v_lshlrev_b32_e32 v242, 16, v148
	v_and_b32_e32 v243, 0xffff0000, v148
	v_lshlrev_b32_e32 v244, 16, v149
	v_and_b32_e32 v245, 0xffff0000, v149
	v_lshlrev_b32_e32 v246, 16, v150
	v_and_b32_e32 v247, 0xffff0000, v150
	v_lshlrev_b32_e32 v198, 16, v151
	v_and_b32_e32 v199, 0xffff0000, v151
	v_pk_add_f32 v[86:87], v[86:87], v[244:245]
	v_pk_add_f32 v[84:85], v[84:85], v[242:243]
	v_pk_add_f32 v[80:81], v[80:81], v[246:247]
	v_pk_add_f32 v[82:83], v[82:83], v[198:199]
	v_cvt_pk_bf16_f32 v242, v84, v85
	v_cvt_pk_bf16_f32 v243, v86, v87
	v_cvt_pk_bf16_f32 v244, v80, v81
	v_cvt_pk_bf16_f32 v245, v82, v83
	global_store_dwordx4 v197, v[242:245], s[64:65] offset:256
	v_mul_f32_e32 v246, v85, v85
	v_mul_f32_e32 v247, v87, v87
	v_fmac_f32_e32 v246, v84, v84
	v_fmac_f32_e32 v247, v86, v86
	v_add_f32_e32 v246, v246, v247
	v_mul_f32_e32 v247, v81, v81
	v_fmac_f32_e32 v247, v80, v80
	v_add_f32_e32 v246, v247, v246
	v_mul_f32_e32 v247, v83, v83
	v_fmac_f32_e32 v247, v82, v82
	v_add_f32_e32 v246, v247, v246
	v_add_f32_e32 v144, v144, v246
	s_waitcnt vmcnt(14)
	v_add_u32_e32 v197, 0x30000, v196
	v_lshlrev_b32_e32 v242, 16, v178
	v_and_b32_e32 v243, 0xffff0000, v178
	v_lshlrev_b32_e32 v244, 16, v179
	v_and_b32_e32 v245, 0xffff0000, v179
	v_lshlrev_b32_e32 v246, 16, v180
	v_and_b32_e32 v247, 0xffff0000, v180
	v_lshlrev_b32_e32 v198, 16, v181
	v_and_b32_e32 v199, 0xffff0000, v181
	v_pk_add_f32 v[78:79], v[78:79], v[244:245]
	v_pk_add_f32 v[76:77], v[76:77], v[242:243]
	v_pk_add_f32 v[72:73], v[72:73], v[246:247]
	v_pk_add_f32 v[74:75], v[74:75], v[198:199]
	v_cvt_pk_bf16_f32 v242, v76, v77
	v_cvt_pk_bf16_f32 v243, v78, v79
	v_cvt_pk_bf16_f32 v244, v72, v73
	v_cvt_pk_bf16_f32 v245, v74, v75
	global_store_dwordx4 v197, v[242:245], s[64:65]
	v_mul_f32_e32 v246, v77, v77
	v_mul_f32_e32 v247, v79, v79
	v_fmac_f32_e32 v246, v76, v76
	v_fmac_f32_e32 v247, v78, v78
	v_add_f32_e32 v246, v246, v247
	v_mul_f32_e32 v247, v73, v73
	v_fmac_f32_e32 v247, v72, v72
	v_add_f32_e32 v246, v247, v246
	v_mul_f32_e32 v247, v75, v75
	v_fmac_f32_e32 v247, v74, v74
	v_add_f32_e32 v178, v247, v246
	v_lshlrev_b32_e32 v242, 16, v182
	v_and_b32_e32 v243, 0xffff0000, v182
	v_lshlrev_b32_e32 v244, 16, v183
	v_and_b32_e32 v245, 0xffff0000, v183
	v_lshlrev_b32_e32 v246, 16, v184
	v_and_b32_e32 v247, 0xffff0000, v184
	v_lshlrev_b32_e32 v198, 16, v185
	v_and_b32_e32 v199, 0xffff0000, v185
	v_pk_add_f32 v[70:71], v[70:71], v[244:245]
	v_pk_add_f32 v[68:69], v[68:69], v[242:243]
	v_pk_add_f32 v[64:65], v[64:65], v[246:247]
	v_pk_add_f32 v[66:67], v[66:67], v[198:199]
	v_cvt_pk_bf16_f32 v242, v68, v69
	v_cvt_pk_bf16_f32 v243, v70, v71
	v_cvt_pk_bf16_f32 v244, v64, v65
	v_cvt_pk_bf16_f32 v245, v66, v67
	global_store_dwordx4 v197, v[242:245], s[64:65] offset:256
	v_mul_f32_e32 v246, v69, v69
	v_mul_f32_e32 v247, v71, v71
	v_fmac_f32_e32 v246, v68, v68
	v_fmac_f32_e32 v247, v70, v70
	v_add_f32_e32 v246, v246, v247
	v_mul_f32_e32 v247, v65, v65
	v_fmac_f32_e32 v247, v64, v64
	v_add_f32_e32 v246, v247, v246
	v_mul_f32_e32 v247, v67, v67
	v_fmac_f32_e32 v247, v66, v66
	v_add_f32_e32 v246, v247, v246
	v_add_f32_e32 v178, v178, v246
	s_waitcnt vmcnt(14)
	v_add_u32_e32 v197, 0x80000, v196
	v_lshlrev_b32_e32 v242, 16, v186
	v_and_b32_e32 v243, 0xffff0000, v186
	v_lshlrev_b32_e32 v244, 16, v187
	v_and_b32_e32 v245, 0xffff0000, v187
	v_lshlrev_b32_e32 v246, 16, v188
	v_and_b32_e32 v247, 0xffff0000, v188
	v_lshlrev_b32_e32 v198, 16, v189
	v_and_b32_e32 v199, 0xffff0000, v189
	v_pk_add_f32 v[62:63], v[62:63], v[244:245]
	v_pk_add_f32 v[60:61], v[60:61], v[242:243]
	v_pk_add_f32 v[56:57], v[56:57], v[246:247]
	v_pk_add_f32 v[58:59], v[58:59], v[198:199]
	v_cvt_pk_bf16_f32 v242, v60, v61
	v_cvt_pk_bf16_f32 v243, v62, v63
	v_cvt_pk_bf16_f32 v244, v56, v57
	v_cvt_pk_bf16_f32 v245, v58, v59
	global_store_dwordx4 v197, v[242:245], s[64:65]
	v_mul_f32_e32 v246, v61, v61
	v_mul_f32_e32 v247, v63, v63
	v_fmac_f32_e32 v246, v60, v60
	v_fmac_f32_e32 v247, v62, v62
	v_add_f32_e32 v246, v246, v247
	v_mul_f32_e32 v247, v57, v57
	v_fmac_f32_e32 v247, v56, v56
	v_add_f32_e32 v246, v247, v246
	v_mul_f32_e32 v247, v59, v59
	v_fmac_f32_e32 v247, v58, v58
	v_add_f32_e32 v186, v247, v246
	v_lshlrev_b32_e32 v242, 16, v214
	v_and_b32_e32 v243, 0xffff0000, v214
	v_lshlrev_b32_e32 v244, 16, v215
	v_and_b32_e32 v245, 0xffff0000, v215
	v_lshlrev_b32_e32 v246, 16, v216
	v_and_b32_e32 v247, 0xffff0000, v216
	v_lshlrev_b32_e32 v198, 16, v217
	v_and_b32_e32 v199, 0xffff0000, v217
	v_pk_add_f32 v[54:55], v[54:55], v[244:245]
	v_pk_add_f32 v[52:53], v[52:53], v[242:243]
	v_pk_add_f32 v[48:49], v[48:49], v[246:247]
	v_pk_add_f32 v[50:51], v[50:51], v[198:199]
	v_cvt_pk_bf16_f32 v242, v52, v53
	v_cvt_pk_bf16_f32 v243, v54, v55
	v_cvt_pk_bf16_f32 v244, v48, v49
	v_cvt_pk_bf16_f32 v245, v50, v51
	global_store_dwordx4 v197, v[242:245], s[64:65] offset:256
	v_mul_f32_e32 v246, v53, v53
	v_mul_f32_e32 v247, v55, v55
	v_fmac_f32_e32 v246, v52, v52
	v_fmac_f32_e32 v247, v54, v54
	v_add_f32_e32 v246, v246, v247
	v_mul_f32_e32 v247, v49, v49
	v_fmac_f32_e32 v247, v48, v48
	v_add_f32_e32 v246, v247, v246
	v_mul_f32_e32 v247, v51, v51
	v_fmac_f32_e32 v247, v50, v50
	v_add_f32_e32 v246, v247, v246
	v_add_f32_e32 v186, v186, v246
	s_waitcnt vmcnt(14)
; __device__ __forceinline__ unsigned cvt_pk_bf16(float lo, float hi) { unsigned r; asm volatile("v_cvt_pk_bf16_f32 %0, %1, %2" : "=v"(r) : "v"(lo), "v"(hi)); return r; }
; __device__ __forceinline__ float bf_lo(unsigned w) { return __uint_as_float(w << 16); }
; __device__ __forceinline__ float bf_hi(unsigned w) { return __uint_as_float(w & 0xffff0000u); }
;     __device__ __forceinline__ void operator()(const f32x4 (&acc)[2][2][4][2], const Unit& u, int wr, int wc, int fr, int fq) const {
;         const int row0 = u.pm * BM + wr * 64 + fr, col0 = u.pn * BM + wc * 32 + 8 * fq;
; #pragma unroll
;         for (int ai = 0; ai < 2; ++ai) {
;             u32x4 xr[4][2];
; #pragma unroll
;             for (int m = 0; m < 4; ++m)
; #pragma unroll
;                 for (int bj = 0; bj < 2; ++bj) xr[m][bj] = *(const u32x4*)(xb + (size_t)(row0 + ai * HALF + m * 16) * ldc + col0 + bj * HALF);
;             asm volatile("" : "+v"(xr[0][0]), "+v"(xr[0][1]), "+v"(xr[1][0]), "+v"(xr[1][1]), "+v"(xr[2][0]), "+v"(xr[2][1]), "+v"(xr[3][0]), "+v"(xr[3][1]));
; #pragma unroll
;             for (int m = 0; m < 4; ++m) { const int row = row0 + ai * HALF + m * 16; const size_t off = (size_t)row * ldc + col0; float s = 0.f;
; #pragma unroll
;                 for (int bj = 0; bj < 2; ++bj) { const u32x4 b = xr[m][bj];
;                     const f32x4 v0 = (f32x4){bf_lo(b.x), bf_hi(b.x), bf_lo(b.y), bf_hi(b.y)} + acc[ai][bj][m][0], v1 = (f32x4){bf_lo(b.z), bf_hi(b.z), bf_lo(b.w), bf_hi(b.w)} + acc[ai][bj][m][1];
;                     u32x4 w; w.x = cvt_pk_bf16(v0[0], v0[1]); w.y = cvt_pk_bf16(v0[2], v0[3]); w.z = cvt_pk_bf16(v1[0], v1[1]); w.w = cvt_pk_bf16(v1[2], v1[3]); *(u32x4*)(xb + off + bj * HALF) = w;
;                     s += (v0[0] * v0[0] + v0[1] * v0[1]) + (v0[2] * v0[2] + v0[3] * v0[3]) + (v1[0] * v1[0] + v1[1] * v1[1]) + (v1[2] * v1[2] + v1[3] * v1[3]); }
;                 s += __shfl_xor(s, 16); s += __shfl_xor(s, 32); if (fq == 0) part[((size_t)u.pm * 32 + u.pn * 4 + wc) * 256 + (row & 255)] = s; }
	v_add_u32_e32 v197, 0x90000, v196
	v_lshlrev_b32_e32 v242, 16, v218
	v_and_b32_e32 v243, 0xffff0000, v218
	v_lshlrev_b32_e32 v244, 16, v219
	v_and_b32_e32 v245, 0xffff0000, v219
	v_lshlrev_b32_e32 v246, 16, v220
	v_and_b32_e32 v247, 0xffff0000, v220
	v_lshlrev_b32_e32 v198, 16, v221
	v_and_b32_e32 v199, 0xffff0000, v221
	v_pk_add_f32 v[46:47], v[46:47], v[244:245]
	v_pk_add_f32 v[44:45], v[44:45], v[242:243]
	v_pk_add_f32 v[40:41], v[40:41], v[246:247]
	v_pk_add_f32 v[42:43], v[42:43], v[198:199]
	v_cvt_pk_bf16_f32 v242, v44, v45
	v_cvt_pk_bf16_f32 v243, v46, v47
	v_cvt_pk_bf16_f32 v244, v40, v41
	v_cvt_pk_bf16_f32 v245, v42, v43
	global_store_dwordx4 v197, v[242:245], s[64:65]
	v_mul_f32_e32 v246, v45, v45
	v_mul_f32_e32 v247, v47, v47
	v_fmac_f32_e32 v246, v44, v44
	v_fmac_f32_e32 v247, v46, v46
	v_add_f32_e32 v246, v246, v247
	v_mul_f32_e32 v247, v41, v41
	v_fmac_f32_e32 v247, v40, v40
	v_add_f32_e32 v246, v247, v246
	v_mul_f32_e32 v247, v43, v43
	v_fmac_f32_e32 v247, v42, v42
	v_add_f32_e32 v218, v247, v246
	v_lshlrev_b32_e32 v242, 16, v222
	v_and_b32_e32 v243, 0xffff0000, v222
	v_lshlrev_b32_e32 v244, 16, v223
	v_and_b32_e32 v245, 0xffff0000, v223
	v_lshlrev_b32_e32 v246, 16, v224
	v_and_b32_e32 v247, 0xffff0000, v224
	v_lshlrev_b32_e32 v198, 16, v225
	v_and_b32_e32 v199, 0xffff0000, v225
	v_pk_add_f32 v[38:39], v[38:39], v[244:245]
	v_pk_add_f32 v[36:37], v[36:37], v[242:243]
	v_pk_add_f32 v[32:33], v[32:33], v[246:247]
	v_pk_add_f32 v[34:35], v[34:35], v[198:199]
	v_cvt_pk_bf16_f32 v242, v36, v37
	v_cvt_pk_bf16_f32 v243, v38, v39
	v_cvt_pk_bf16_f32 v244, v32, v33
	v_cvt_pk_bf16_f32 v245, v34, v35
	global_store_dwordx4 v197, v[242:245], s[64:65] offset:256
	v_mul_f32_e32 v246, v37, v37
	v_mul_f32_e32 v247, v39, v39
	v_fmac_f32_e32 v246, v36, v36
	v_fmac_f32_e32 v247, v38, v38
	v_add_f32_e32 v246, v246, v247
	v_mul_f32_e32 v247, v33, v33
	v_fmac_f32_e32 v247, v32, v32
	v_add_f32_e32 v246, v247, v246
	v_mul_f32_e32 v247, v35, v35
	v_fmac_f32_e32 v247, v34, v34
	v_add_f32_e32 v246, v247, v246
	v_add_f32_e32 v218, v218, v246
	s_waitcnt vmcnt(14)
	v_add_u32_e32 v197, 0xa0000, v196
	v_lshlrev_b32_e32 v242, 16, v226
	v_and_b32_e32 v243, 0xffff0000, v226
	v_lshlrev_b32_e32 v244, 16, v227
	v_and_b32_e32 v245, 0xffff0000, v227
	v_lshlrev_b32_e32 v246, 16, v228
	v_and_b32_e32 v247, 0xffff0000, v228
	v_lshlrev_b32_e32 v198, 16, v229
	v_and_b32_e32 v199, 0xffff0000, v229
	v_pk_add_f32 v[30:31], v[30:31], v[244:245]
	v_pk_add_f32 v[28:29], v[28:29], v[242:243]
	v_pk_add_f32 v[24:25], v[24:25], v[246:247]
	v_pk_add_f32 v[26:27], v[26:27], v[198:199]
	v_cvt_pk_bf16_f32 v242, v28, v29
	v_cvt_pk_bf16_f32 v243, v30, v31
	v_cvt_pk_bf16_f32 v244, v24, v25
	v_cvt_pk_bf16_f32 v245, v26, v27
	global_store_dwordx4 v197, v[242:245], s[64:65]
	v_mul_f32_e32 v246, v29, v29
	v_mul_f32_e32 v247, v31, v31
	v_fmac_f32_e32 v246, v28, v28
	v_fmac_f32_e32 v247, v30, v30
	v_add_f32_e32 v246, v246, v247
	v_mul_f32_e32 v247, v25, v25
	v_fmac_f32_e32 v247, v24, v24
	v_add_f32_e32 v246, v247, v246
	v_mul_f32_e32 v247, v27, v27
	v_fmac_f32_e32 v247, v26, v26
	v_add_f32_e32 v226, v247, v246
	v_lshlrev_b32_e32 v242, 16, v230
	v_and_b32_e32 v243, 0xffff0000, v230
	v_lshlrev_b32_e32 v244, 16, v231
	v_and_b32_e32 v245, 0xffff0000, v231
	v_lshlrev_b32_e32 v246, 16, v232
	v_and_b32_e32 v247, 0xffff0000, v232
	v_lshlrev_b32_e32 v198, 16, v233
	v_and_b32_e32 v199, 0xffff0000, v233
	v_pk_add_f32 v[22:23], v[22:23], v[244:245]
	v_pk_add_f32 v[20:21], v[20:21], v[242:243]
	v_pk_add_f32 v[16:17], v[16:17], v[246:247]
	v_pk_add_f32 v[18:19], v[18:19], v[198:199]
	v_cvt_pk_bf16_f32 v242, v20, v21
	v_cvt_pk_bf16_f32 v243, v22, v23
	v_cvt_pk_bf16_f32 v244, v16, v17
	v_cvt_pk_bf16_f32 v245, v18, v19
	global_store_dwordx4 v197, v[242:245], s[64:65] offset:256
	v_mul_f32_e32 v246, v21, v21
	v_mul_f32_e32 v247, v23, v23
	v_fmac_f32_e32 v246, v20, v20
	v_fmac_f32_e32 v247, v22, v22
	v_add_f32_e32 v246, v246, v247
	v_mul_f32_e32 v247, v17, v17
	v_fmac_f32_e32 v247, v16, v16
	v_add_f32_e32 v246, v247, v246
	v_mul_f32_e32 v247, v19, v19
	v_fmac_f32_e32 v247, v18, v18
	v_add_f32_e32 v246, v247, v246
	v_add_f32_e32 v226, v226, v246
	s_waitcnt vmcnt(14)
; __device__ __forceinline__ unsigned cvt_pk_bf16(float lo, float hi) { unsigned r; asm volatile("v_cvt_pk_bf16_f32 %0, %1, %2" : "=v"(r) : "v"(lo), "v"(hi)); return r; }
; __device__ __forceinline__ float bf_lo(unsigned w) { return __uint_as_float(w << 16); }
; __device__ __forceinline__ float bf_hi(unsigned w) { return __uint_as_float(w & 0xffff0000u); }
;     __device__ __forceinline__ void operator()(const f32x4 (&acc)[2][2][4][2], const Unit& u, int wr, int wc, int fr, int fq) const {
;     ...
;                 for (int bj = 0; bj < 2; ++bj) { const u32x4 b = xr[m][bj];
;                     const f32x4 v0 = (f32x4){bf_lo(b.x), bf_hi(b.x), bf_lo(b.y), bf_hi(b.y)} + acc[ai][bj][m][0], v1 = (f32x4){bf_lo(b.z), bf_hi(b.z), bf_lo(b.w), bf_hi(b.w)} + acc[ai][bj][m][1];
;                     u32x4 w; w.x = cvt_pk_bf16(v0[0], v0[1]); w.y = cvt_pk_bf16(v0[2], v0[3]); w.z = cvt_pk_bf16(v1[0], v1[1]); w.w = cvt_pk_bf16(v1[2], v1[3]); *(u32x4*)(xb + off + bj * HALF) = w;
;                     s += (v0[0] * v0[0] + v0[1] * v0[1]) + (v0[2] * v0[2] + v0[3] * v0[3]) + (v1[0] * v1[0] + v1[1] * v1[1]) + (v1[2] * v1[2] + v1[3] * v1[3]); }
;                 s += __shfl_xor(s, 16); s += __shfl_xor(s, 32); if (fq == 0) part[((size_t)u.pm * 32 + u.pn * 4 + wc) * 256 + (row & 255)] = s; }
	v_add_u32_e32 v197, 0xb0000, v196
	v_lshlrev_b32_e32 v242, 16, v234
	v_and_b32_e32 v243, 0xffff0000, v234
	v_lshlrev_b32_e32 v244, 16, v235
	v_and_b32_e32 v245, 0xffff0000, v235
	v_lshlrev_b32_e32 v246, 16, v236
	v_and_b32_e32 v247, 0xffff0000, v236
	v_lshlrev_b32_e32 v198, 16, v237
	v_and_b32_e32 v199, 0xffff0000, v237
	v_pk_add_f32 v[14:15], v[14:15], v[244:245]
	v_pk_add_f32 v[12:13], v[12:13], v[242:243]
	v_pk_add_f32 v[8:9], v[8:9], v[246:247]
	v_pk_add_f32 v[10:11], v[10:11], v[198:199]
	v_cvt_pk_bf16_f32 v242, v12, v13
	v_cvt_pk_bf16_f32 v243, v14, v15
	v_cvt_pk_bf16_f32 v244, v8, v9
	v_cvt_pk_bf16_f32 v245, v10, v11
	global_store_dwordx4 v197, v[242:245], s[64:65]
	v_mul_f32_e32 v246, v13, v13
	v_mul_f32_e32 v247, v15, v15
	v_fmac_f32_e32 v246, v12, v12
	v_fmac_f32_e32 v247, v14, v14
	v_add_f32_e32 v246, v246, v247
	v_mul_f32_e32 v247, v9, v9
	v_fmac_f32_e32 v247, v8, v8
	v_add_f32_e32 v246, v247, v246
	v_mul_f32_e32 v247, v11, v11
	v_fmac_f32_e32 v247, v10, v10
	v_add_f32_e32 v234, v247, v246
	v_lshlrev_b32_e32 v242, 16, v238
	v_and_b32_e32 v243, 0xffff0000, v238
	v_lshlrev_b32_e32 v244, 16, v239
	v_and_b32_e32 v245, 0xffff0000, v239
	v_lshlrev_b32_e32 v246, 16, v240
	v_and_b32_e32 v247, 0xffff0000, v240
	v_lshlrev_b32_e32 v198, 16, v241
	v_and_b32_e32 v199, 0xffff0000, v241
	v_pk_add_f32 v[6:7], v[6:7], v[244:245]
	v_pk_add_f32 v[4:5], v[4:5], v[242:243]
	v_pk_add_f32 v[0:1], v[0:1], v[246:247]
	v_pk_add_f32 v[2:3], v[2:3], v[198:199]
	v_cvt_pk_bf16_f32 v242, v4, v5
	v_cvt_pk_bf16_f32 v243, v6, v7
	v_cvt_pk_bf16_f32 v244, v0, v1
	v_cvt_pk_bf16_f32 v245, v2, v3
	global_store_dwordx4 v197, v[242:245], s[64:65] offset:256
	v_mul_f32_e32 v246, v5, v5
	v_mul_f32_e32 v247, v7, v7
	v_fmac_f32_e32 v246, v4, v4
	v_fmac_f32_e32 v247, v6, v6
	v_add_f32_e32 v246, v246, v247
	v_mul_f32_e32 v247, v1, v1
	v_fmac_f32_e32 v247, v0, v0
	v_add_f32_e32 v246, v247, v246
	v_mul_f32_e32 v247, v3, v3
	v_fmac_f32_e32 v247, v2, v2
	v_add_f32_e32 v246, v247, v246
	v_add_f32_e32 v234, v234, v246
	ds_bpermute_b32 v129, v208, v128
	ds_bpermute_b32 v137, v208, v136
	ds_bpermute_b32 v145, v208, v144
	ds_bpermute_b32 v179, v208, v178
	ds_bpermute_b32 v187, v208, v186
	ds_bpermute_b32 v219, v208, v218
	ds_bpermute_b32 v227, v208, v226
	ds_bpermute_b32 v235, v208, v234
	v_add_u32_e32 v130, 0, v210
	v_add_u32_e32 v138, 16, v210
	v_add_u32_e32 v146, 32, v210
	v_add_u32_e32 v180, 48, v210
	v_add_u32_e32 v188, 128, v210
	v_add_u32_e32 v220, 144, v210
	v_add_u32_e32 v228, 160, v210
	v_add_u32_e32 v236, 176, v210
	s_waitcnt lgkmcnt(0)
	v_add_f32_e32 v128, v128, v129
	v_add_f32_e32 v136, v136, v137
	v_add_f32_e32 v144, v144, v145
	v_add_f32_e32 v178, v178, v179
	v_add_f32_e32 v186, v186, v187
	v_add_f32_e32 v218, v218, v219
	v_add_f32_e32 v226, v226, v227
	v_add_f32_e32 v234, v234, v235
	ds_bpermute_b32 v129, v209, v128
	ds_bpermute_b32 v137, v209, v136
	ds_bpermute_b32 v145, v209, v144
	ds_bpermute_b32 v179, v209, v178
	ds_bpermute_b32 v187, v209, v186
	ds_bpermute_b32 v219, v209, v218
	ds_bpermute_b32 v227, v209, v226
	ds_bpermute_b32 v235, v209, v234
	v_lshlrev_b32_e32 v130, 2, v130
	v_lshlrev_b32_e32 v138, 2, v138
	v_lshlrev_b32_e32 v146, 2, v146
	v_lshlrev_b32_e32 v180, 2, v180
	v_lshlrev_b32_e32 v188, 2, v188
	v_lshlrev_b32_e32 v220, 2, v220
	v_lshlrev_b32_e32 v228, 2, v228
	v_lshlrev_b32_e32 v236, 2, v236
	s_add_u32 s46, s54, s94
	s_addc_u32 s47, s55, s95
	s_waitcnt lgkmcnt(0)
	v_add_f32_e32 v128, v128, v129
	v_add_f32_e32 v136, v136, v137
	v_add_f32_e32 v144, v144, v145
	v_add_f32_e32 v178, v178, v179
	v_add_f32_e32 v186, v186, v187
	v_add_f32_e32 v218, v218, v219
	v_add_f32_e32 v226, v226, v227
	v_add_f32_e32 v234, v234, v235
	s_and_saveexec_b64 s[28:29], s[40:41]
	global_store_dword v130, v128, s[46:47]
	global_store_dword v138, v136, s[46:47]
	global_store_dword v146, v144, s[46:47]
	global_store_dword v180, v178, s[46:47]
	global_store_dword v188, v186, s[46:47]
	global_store_dword v220, v218, s[46:47]
	global_store_dword v228, v226, s[46:47]
	global_store_dword v236, v234, s[46:47]

; __device__ __forceinline__ unsigned cvt_pk_bf16(float lo, float hi) { unsigned r; asm volatile("v_cvt_pk_bf16_f32 %0, %1, %2" : "=v"(r) : "v"(lo), "v"(hi)); return r; }
; __device__ __forceinline__ float bf_lo(unsigned w) { return __uint_as_float(w << 16); }
; __device__ __forceinline__ float bf_hi(unsigned w) { return __uint_as_float(w & 0xffff0000u); }
;     __device__ __forceinline__ void operator()(const f32x4 (&acc)[2][2][4][2], const Unit& u, int wr, int wc, int fr, int fq) const {
;     ...
;         for (int ai = 0; ai < 2; ++ai) {
;             u32x4 xr[4][2];
; #pragma unroll
;             for (int m = 0; m < 4; ++m)
; #pragma unroll
;                 for (int bj = 0; bj < 2; ++bj) xr[m][bj] = *(const u32x4*)(xb + (size_t)(row0 + ai * HALF + m * 16) * ldc + col0 + bj * HALF);
;             asm volatile("" : "+v"(xr[0][0]), "+v"(xr[0][1]), "+v"(xr[1][0]), "+v"(xr[1][1]), "+v"(xr[2][0]), "+v"(xr[2][1]), "+v"(xr[3][0]), "+v"(xr[3][1]));
; #pragma unroll
;             for (int m = 0; m < 4; ++m) { const int row = row0 + ai * HALF + m * 16; const size_t off = (size_t)row * ldc + col0; float s = 0.f;
; #pragma unroll
;                 for (int bj = 0; bj < 2; ++bj) { const u32x4 b = xr[m][bj];
;                     const f32x4 v0 = (f32x4){bf_lo(b.x), bf_hi(b.x), bf_lo(b.y), bf_hi(b.y)} + acc[ai][bj][m][0], v1 = (f32x4){bf_lo(b.z), bf_hi(b.z), bf_lo(b.w), bf_hi(b.w)} + acc[ai][bj][m][1];
;                     u32x4 w; w.x = cvt_pk_bf16(v0[0], v0[1]); w.y = cvt_pk_bf16(v0[2], v0[3]); w.z = cvt_pk_bf16(v1[0], v1[1]); w.w = cvt_pk_bf16(v1[2], v1[3]); *(u32x4*)(xb + off + bj * HALF) = w;
;                     s += (v0[0] * v0[0] + v0[1] * v0[1]) + (v0[2] * v0[2] + v0[3] * v0[3]) + (v1[0] * v1[0] + v1[1] * v1[1]) + (v1[2] * v1[2] + v1[3] * v1[3]); }
.LBB0_409:
	v_lshl_or_b32 v197, s77, 8, v212
	v_lshl_add_u32 v196, s90, 8, v210
	v_lshlrev_b32_e32 v196, 12, v196
	v_lshl_add_u32 v196, v197, 1, v196
	v_mov_b32_e32 v197, v196
	global_load_dwordx4 v[128:131], v197, s[64:65]
	global_load_dwordx4 v[132:135], v197, s[64:65] offset:256
	v_add_u32_e32 v197, 0x10000, v196
	global_load_dwordx4 v[136:139], v197, s[64:65]
	global_load_dwordx4 v[140:143], v197, s[64:65] offset:256
	v_add_u32_e32 v197, 0x20000, v196
	global_load_dwordx4 v[144:147], v197, s[64:65]
	global_load_dwordx4 v[148:151], v197, s[64:65] offset:256
	v_add_u32_e32 v197, 0x30000, v196
	global_load_dwordx4 v[178:181], v197, s[64:65]
	global_load_dwordx4 v[182:185], v197, s[64:65] offset:256
	v_add_u32_e32 v197, 0x80000, v196
	global_load_dwordx4 v[186:189], v197, s[64:65]
	global_load_dwordx4 v[214:217], v197, s[64:65] offset:256
	v_add_u32_e32 v197, 0x90000, v196
	global_load_dwordx4 v[218:221], v197, s[64:65]
	global_load_dwordx4 v[222:225], v197, s[64:65] offset:256
	v_add_u32_e32 v197, 0xa0000, v196
	global_load_dwordx4 v[226:229], v197, s[64:65]
	global_load_dwordx4 v[230:233], v197, s[64:65] offset:256
	v_add_u32_e32 v197, 0xb0000, v196
	global_load_dwordx4 v[234:237], v197, s[64:65]
	global_load_dwordx4 v[238:241], v197, s[64:65] offset:256
	s_ashr_i32 s91, s90, 31
	s_lshl_b32 s28, s77, 2
	s_lshl_b64 s[20:21], s[90:91], 5
	s_ashr_i32 s29, s28, 31
	s_add_u32 s20, s20, s28
	s_addc_u32 s21, s21, s29
	s_or_b64 s[20:21], s[20:21], s[12:13]
	s_lshl_b64 s[90:91], s[20:21], 10
	s_waitcnt vmcnt(14)
	v_mov_b32_e32 v197, v196
	v_lshlrev_b32_e32 v242, 16, v128
	v_and_b32_e32 v243, 0xffff0000, v128
	v_lshlrev_b32_e32 v244, 16, v129
	v_and_b32_e32 v245, 0xffff0000, v129
	v_lshlrev_b32_e32 v246, 16, v130
	v_and_b32_e32 v247, 0xffff0000, v130
	v_lshlrev_b32_e32 v198, 16, v131
	v_and_b32_e32 v199, 0xffff0000, v131
	v_pk_add_f32 v[126:127], v[126:127], v[244:245]
	v_pk_add_f32 v[124:125], v[124:125], v[242:243]
	v_pk_add_f32 v[120:121], v[120:121], v[246:247]
	v_pk_add_f32 v[122:123], v[122:123], v[198:199]
	v_cvt_pk_bf16_f32 v242, v124, v125
	v_cvt_pk_bf16_f32 v243, v126, v127
	v_cvt_pk_bf16_f32 v244, v120, v121
	v_cvt_pk_bf16_f32 v245, v122, v123
	global_store_dwordx4 v197, v[242:245], s[64:65]
	v_mul_f32_e32 v246, v125, v125
	v_mul_f32_e32 v247, v127, v127
	v_fmac_f32_e32 v246, v124, v124
	v_fmac_f32_e32 v247, v126, v126
	v_add_f32_e32 v246, v246, v247
	v_mul_f32_e32 v247, v121, v121
	v_fmac_f32_e32 v247, v120, v120
	v_add_f32_e32 v246, v247, v246
	v_mul_f32_e32 v247, v123, v123
	v_fmac_f32_e32 v247, v122, v122
	v_add_f32_e32 v128, v247, v246
	v_lshlrev_b32_e32 v242, 16, v132
	v_and_b32_e32 v243, 0xffff0000, v132
	v_lshlrev_b32_e32 v244, 16, v133
	v_and_b32_e32 v245, 0xffff0000, v133
	v_lshlrev_b32_e32 v246, 16, v134
	v_and_b32_e32 v247, 0xffff0000, v134
	v_lshlrev_b32_e32 v198, 16, v135
	v_and_b32_e32 v199, 0xffff0000, v135
	v_pk_add_f32 v[118:119], v[118:119], v[244:245]
	v_pk_add_f32 v[116:117], v[116:117], v[242:243]
	v_pk_add_f32 v[112:113], v[112:113], v[246:247]
	v_pk_add_f32 v[114:115], v[114:115], v[198:199]
	v_cvt_pk_bf16_f32 v242, v116, v117
	v_cvt_pk_bf16_f32 v243, v118, v119
	v_cvt_pk_bf16_f32 v244, v112, v113
	v_cvt_pk_bf16_f32 v245, v114, v115
	global_store_dwordx4 v197, v[242:245], s[64:65] offset:256
	v_mul_f32_e32 v246, v117, v117
	v_mul_f32_e32 v247, v119, v119
	v_fmac_f32_e32 v246, v116, v116
	v_fmac_f32_e32 v247, v118, v118
	v_add_f32_e32 v246, v246, v247
	v_mul_f32_e32 v247, v113, v113
	v_fmac_f32_e32 v247, v112, v112
	v_add_f32_e32 v246, v247, v246
	v_mul_f32_e32 v247, v115, v115
	v_fmac_f32_e32 v247, v114, v114
	v_add_f32_e32 v246, v247, v246
	v_add_f32_e32 v128, v128, v246
	s_waitcnt vmcnt(14)
	v_add_u32_e32 v197, 0x10000, v196
	v_lshlrev_b32_e32 v242, 16, v136
	v_and_b32_e32 v243, 0xffff0000, v136
	v_lshlrev_b32_e32 v244, 16, v137
	v_and_b32_e32 v245, 0xffff0000, v137
	v_lshlrev_b32_e32 v246, 16, v138
	v_and_b32_e32 v247, 0xffff0000, v138
	v_lshlrev_b32_e32 v198, 16, v139
	v_and_b32_e32 v199, 0xffff0000, v139
	v_pk_add_f32 v[110:111], v[110:111], v[244:245]
	v_pk_add_f32 v[108:109], v[108:109], v[242:243]
	v_pk_add_f32 v[104:105], v[104:105], v[246:247]
	v_pk_add_f32 v[106:107], v[106:107], v[198:199]
	v_cvt_pk_bf16_f32 v242, v108, v109
	v_cvt_pk_bf16_f32 v243, v110, v111
	v_cvt_pk_bf16_f32 v244, v104, v105
	v_cvt_pk_bf16_f32 v245, v106, v107
	global_store_dwordx4 v197, v[242:245], s[64:65]
	v_mul_f32_e32 v246, v109, v109
	v_mul_f32_e32 v247, v111, v111
	v_fmac_f32_e32 v246, v108, v108
	v_fmac_f32_e32 v247, v110, v110
	v_add_f32_e32 v246, v246, v247
	v_mul_f32_e32 v247, v105, v105
	v_fmac_f32_e32 v247, v104, v104
	v_add_f32_e32 v246, v247, v246
	v_mul_f32_e32 v247, v107, v107
	v_fmac_f32_e32 v247, v106, v106
	v_add_f32_e32 v136, v247, v246
	v_lshlrev_b32_e32 v242, 16, v140
	v_and_b32_e32 v243, 0xffff0000, v140
	v_lshlrev_b32_e32 v244, 16, v141
	v_and_b32_e32 v245, 0xffff0000, v141
	v_lshlrev_b32_e32 v246, 16, v142
	v_and_b32_e32 v247, 0xffff0000, v142
	v_lshlrev_b32_e32 v198, 16, v143
	v_and_b32_e32 v199, 0xffff0000, v143
	v_pk_add_f32 v[102:103], v[102:103], v[244:245]
	v_pk_add_f32 v[100:101], v[100:101], v[242:243]
	v_pk_add_f32 v[96:97], v[96:97], v[246:247]
	v_pk_add_f32 v[98:99], v[98:99], v[198:199]
	v_cvt_pk_bf16_f32 v242, v100, v101
	v_cvt_pk_bf16_f32 v243, v102, v103
	v_cvt_pk_bf16_f32 v244, v96, v97
	v_cvt_pk_bf16_f32 v245, v98, v99
	global_store_dwordx4 v197, v[242:245], s[64:65] offset:256
	v_mul_f32_e32 v246, v101, v101
	v_mul_f32_e32 v247, v103, v103
	v_fmac_f32_e32 v246, v100, v100
	v_fmac_f32_e32 v247, v102, v102
	v_add_f32_e32 v246, v246, v247
	v_mul_f32_e32 v247, v97, v97
	v_fmac_f32_e32 v247, v96, v96
	v_add_f32_e32 v246, v247, v246
	v_mul_f32_e32 v247, v99, v99
	v_fmac_f32_e32 v247, v98, v98
	v_add_f32_e32 v246, v247, v246
	v_add_f32_e32 v136, v136, v246
	s_waitcnt vmcnt(14)
; __device__ __forceinline__ unsigned cvt_pk_bf16(float lo, float hi) { unsigned r; asm volatile("v_cvt_pk_bf16_f32 %0, %1, %2" : "=v"(r) : "v"(lo), "v"(hi)); return r; }
; __device__ __forceinline__ float bf_lo(unsigned w) { return __uint_as_float(w << 16); }
; __device__ __forceinline__ float bf_hi(unsigned w) { return __uint_as_float(w & 0xffff0000u); }
;     __device__ __forceinline__ void operator()(const f32x4 (&acc)[2][2][4][2], const Unit& u, int wr, int wc, int fr, int fq) const {
;     ...
;             for (int m = 0; m < 4; ++m) { const int row = row0 + ai * HALF + m * 16; const size_t off = (size_t)row * ldc + col0; float s = 0.f;
; #pragma unroll
;                 for (int bj = 0; bj < 2; ++bj) { const u32x4 b = xr[m][bj];
;                     const f32x4 v0 = (f32x4){bf_lo(b.x), bf_hi(b.x), bf_lo(b.y), bf_hi(b.y)} + acc[ai][bj][m][0], v1 = (f32x4){bf_lo(b.z), bf_hi(b.z), bf_lo(b.w), bf_hi(b.w)} + acc[ai][bj][m][1];
;                     u32x4 w; w.x = cvt_pk_bf16(v0[0], v0[1]); w.y = cvt_pk_bf16(v0[2], v0[3]); w.z = cvt_pk_bf16(v1[0], v1[1]); w.w = cvt_pk_bf16(v1[2], v1[3]); *(u32x4*)(xb + off + bj * HALF) = w;
;                     s += (v0[0] * v0[0] + v0[1] * v0[1]) + (v0[2] * v0[2] + v0[3] * v0[3]) + (v1[0] * v1[0] + v1[1] * v1[1]) + (v1[2] * v1[2] + v1[3] * v1[3]); }
	v_add_u32_e32 v197, 0x20000, v196
	v_lshlrev_b32_e32 v242, 16, v144
	v_and_b32_e32 v243, 0xffff0000, v144
	v_lshlrev_b32_e32 v244, 16, v145
	v_and_b32_e32 v245, 0xffff0000, v145
	v_lshlrev_b32_e32 v246, 16, v146
	v_and_b32_e32 v247, 0xffff0000, v146
	v_lshlrev_b32_e32 v198, 16, v147
	v_and_b32_e32 v199, 0xffff0000, v147
	v_pk_add_f32 v[94:95], v[94:95], v[244:245]
	v_pk_add_f32 v[92:93], v[92:93], v[242:243]
	v_pk_add_f32 v[88:89], v[88:89], v[246:247]
	v_pk_add_f32 v[90:91], v[90:91], v[198:199]
	v_cvt_pk_bf16_f32 v242, v92, v93
	v_cvt_pk_bf16_f32 v243, v94, v95
	v_cvt_pk_bf16_f32 v244, v88, v89
	v_cvt_pk_bf16_f32 v245, v90, v91
	global_store_dwordx4 v197, v[242:245], s[64:65]
	v_mul_f32_e32 v246, v93, v93
	v_mul_f32_e32 v247, v95, v95
	v_fmac_f32_e32 v246, v92, v92
	v_fmac_f32_e32 v247, v94, v94
	v_add_f32_e32 v246, v246, v247
	v_mul_f32_e32 v247, v89, v89
	v_fmac_f32_e32 v247, v88, v88
	v_add_f32_e32 v246, v247, v246
	v_mul_f32_e32 v247, v91, v91
	v_fmac_f32_e32 v247, v90, v90
	v_add_f32_e32 v144, v247, v246
	v_lshlrev_b32_e32 v242, 16, v148
	v_and_b32_e32 v243, 0xffff0000, v148
	v_lshlrev_b32_e32 v244, 16, v149
	v_and_b32_e32 v245, 0xffff0000, v149
	v_lshlrev_b32_e32 v246, 16, v150
	v_and_b32_e32 v247, 0xffff0000, v150
	v_lshlrev_b32_e32 v198, 16, v151
	v_and_b32_e32 v199, 0xffff0000, v151
	v_pk_add_f32 v[86:87], v[86:87], v[244:245]
	v_pk_add_f32 v[84:85], v[84:85], v[242:243]
	v_pk_add_f32 v[80:81], v[80:81], v[246:247]
	v_pk_add_f32 v[82:83], v[82:83], v[198:199]
	v_cvt_pk_bf16_f32 v242, v84, v85
	v_cvt_pk_bf16_f32 v243, v86, v87
	v_cvt_pk_bf16_f32 v244, v80, v81
	v_cvt_pk_bf16_f32 v245, v82, v83
	global_store_dwordx4 v197, v[242:245], s[64:65] offset:256
	v_mul_f32_e32 v246, v85, v85
	v_mul_f32_e32 v247, v87, v87
	v_fmac_f32_e32 v246, v84, v84
	v_fmac_f32_e32 v247, v86, v86
	v_add_f32_e32 v246, v246, v247
	v_mul_f32_e32 v247, v81, v81
	v_fmac_f32_e32 v247, v80, v80
	v_add_f32_e32 v246, v247, v246
	v_mul_f32_e32 v247, v83, v83
	v_fmac_f32_e32 v247, v82, v82
	v_add_f32_e32 v246, v247, v246
	v_add_f32_e32 v144, v144, v246
	s_waitcnt vmcnt(14)
	v_add_u32_e32 v197, 0x30000, v196
	v_lshlrev_b32_e32 v242, 16, v178
	v_and_b32_e32 v243, 0xffff0000, v178
	v_lshlrev_b32_e32 v244, 16, v179
	v_and_b32_e32 v245, 0xffff0000, v179
	v_lshlrev_b32_e32 v246, 16, v180
	v_and_b32_e32 v247, 0xffff0000, v180
	v_lshlrev_b32_e32 v198, 16, v181
	v_and_b32_e32 v199, 0xffff0000, v181
	v_pk_add_f32 v[78:79], v[78:79], v[244:245]
	v_pk_add_f32 v[76:77], v[76:77], v[242:243]
	v_pk_add_f32 v[72:73], v[72:73], v[246:247]
	v_pk_add_f32 v[74:75], v[74:75], v[198:199]
	v_cvt_pk_bf16_f32 v242, v76, v77
	v_cvt_pk_bf16_f32 v243, v78, v79
	v_cvt_pk_bf16_f32 v244, v72, v73
	v_cvt_pk_bf16_f32 v245, v74, v75
	global_store_dwordx4 v197, v[242:245], s[64:65]
	v_mul_f32_e32 v246, v77, v77
	v_mul_f32_e32 v247, v79, v79
	v_fmac_f32_e32 v246, v76, v76
	v_fmac_f32_e32 v247, v78, v78
	v_add_f32_e32 v246, v246, v247
	v_mul_f32_e32 v247, v73, v73
	v_fmac_f32_e32 v247, v72, v72
	v_add_f32_e32 v246, v247, v246
	v_mul_f32_e32 v247, v75, v75
	v_fmac_f32_e32 v247, v74, v74
	v_add_f32_e32 v178, v247, v246
	v_lshlrev_b32_e32 v242, 16, v182
	v_and_b32_e32 v243, 0xffff0000, v182
	v_lshlrev_b32_e32 v244, 16, v183
	v_and_b32_e32 v245, 0xffff0000, v183
	v_lshlrev_b32_e32 v246, 16, v184
	v_and_b32_e32 v247, 0xffff0000, v184
	v_lshlrev_b32_e32 v198, 16, v185
	v_and_b32_e32 v199, 0xffff0000, v185
	v_pk_add_f32 v[70:71], v[70:71], v[244:245]
	v_pk_add_f32 v[68:69], v[68:69], v[242:243]
	v_pk_add_f32 v[64:65], v[64:65], v[246:247]
	v_pk_add_f32 v[66:67], v[66:67], v[198:199]
	v_cvt_pk_bf16_f32 v242, v68, v69
	v_cvt_pk_bf16_f32 v243, v70, v71
	v_cvt_pk_bf16_f32 v244, v64, v65
	v_cvt_pk_bf16_f32 v245, v66, v67
	global_store_dwordx4 v197, v[242:245], s[64:65] offset:256
	v_mul_f32_e32 v246, v69, v69
	v_mul_f32_e32 v247, v71, v71
	v_fmac_f32_e32 v246, v68, v68
	v_fmac_f32_e32 v247, v70, v70
	v_add_f32_e32 v246, v246, v247
	v_mul_f32_e32 v247, v65, v65
	v_fmac_f32_e32 v247, v64, v64
	v_add_f32_e32 v246, v247, v246
	v_mul_f32_e32 v247, v67, v67
	v_fmac_f32_e32 v247, v66, v66
	v_add_f32_e32 v246, v247, v246
	v_add_f32_e32 v178, v178, v246
	s_waitcnt vmcnt(14)
	v_add_u32_e32 v197, 0x80000, v196
	v_lshlrev_b32_e32 v242, 16, v186
	v_and_b32_e32 v243, 0xffff0000, v186
	v_lshlrev_b32_e32 v244, 16, v187
	v_and_b32_e32 v245, 0xffff0000, v187
	v_lshlrev_b32_e32 v246, 16, v188
	v_and_b32_e32 v247, 0xffff0000, v188
	v_lshlrev_b32_e32 v198, 16, v189
	v_and_b32_e32 v199, 0xffff0000, v189
	v_pk_add_f32 v[62:63], v[62:63], v[244:245]
	v_pk_add_f32 v[60:61], v[60:61], v[242:243]
	v_pk_add_f32 v[56:57], v[56:57], v[246:247]
	v_pk_add_f32 v[58:59], v[58:59], v[198:199]
	v_cvt_pk_bf16_f32 v242, v60, v61
	v_cvt_pk_bf16_f32 v243, v62, v63
	v_cvt_pk_bf16_f32 v244, v56, v57
	v_cvt_pk_bf16_f32 v245, v58, v59
	global_store_dwordx4 v197, v[242:245], s[64:65]
	v_mul_f32_e32 v246, v61, v61
	v_mul_f32_e32 v247, v63, v63
	v_fmac_f32_e32 v246, v60, v60
	v_fmac_f32_e32 v247, v62, v62
	v_add_f32_e32 v246, v246, v247
	v_mul_f32_e32 v247, v57, v57
	v_fmac_f32_e32 v247, v56, v56
	v_add_f32_e32 v246, v247, v246
	v_mul_f32_e32 v247, v59, v59
	v_fmac_f32_e32 v247, v58, v58
	v_add_f32_e32 v186, v247, v246
	v_lshlrev_b32_e32 v242, 16, v214
	v_and_b32_e32 v243, 0xffff0000, v214
	v_lshlrev_b32_e32 v244, 16, v215
	v_and_b32_e32 v245, 0xffff0000, v215
	v_lshlrev_b32_e32 v246, 16, v216
	v_and_b32_e32 v247, 0xffff0000, v216
	v_lshlrev_b32_e32 v198, 16, v217
	v_and_b32_e32 v199, 0xffff0000, v217
	v_pk_add_f32 v[54:55], v[54:55], v[244:245]
	v_pk_add_f32 v[52:53], v[52:53], v[242:243]
	v_pk_add_f32 v[48:49], v[48:49], v[246:247]
	v_pk_add_f32 v[50:51], v[50:51], v[198:199]
	v_cvt_pk_bf16_f32 v242, v52, v53
	v_cvt_pk_bf16_f32 v243, v54, v55
	v_cvt_pk_bf16_f32 v244, v48, v49
	v_cvt_pk_bf16_f32 v245, v50, v51
	global_store_dwordx4 v197, v[242:245], s[64:65] offset:256
	v_mul_f32_e32 v246, v53, v53
	v_mul_f32_e32 v247, v55, v55
	v_fmac_f32_e32 v246, v52, v52
	v_fmac_f32_e32 v247, v54, v54
	v_add_f32_e32 v246, v246, v247
	v_mul_f32_e32 v247, v49, v49
	v_fmac_f32_e32 v247, v48, v48
	v_add_f32_e32 v246, v247, v246
	v_mul_f32_e32 v247, v51, v51
	v_fmac_f32_e32 v247, v50, v50
	v_add_f32_e32 v246, v247, v246
	v_add_f32_e32 v186, v186, v246
	s_waitcnt vmcnt(14)
; __device__ __forceinline__ unsigned cvt_pk_bf16(float lo, float hi) { unsigned r; asm volatile("v_cvt_pk_bf16_f32 %0, %1, %2" : "=v"(r) : "v"(lo), "v"(hi)); return r; }
; __device__ __forceinline__ float bf_lo(unsigned w) { return __uint_as_float(w << 16); }
; __device__ __forceinline__ float bf_hi(unsigned w) { return __uint_as_float(w & 0xffff0000u); }
;     __device__ __forceinline__ void operator()(const f32x4 (&acc)[2][2][4][2], const Unit& u, int wr, int wc, int fr, int fq) const {
;     ...
;             for (int m = 0; m < 4; ++m) { const int row = row0 + ai * HALF + m * 16; const size_t off = (size_t)row * ldc + col0; float s = 0.f;
; #pragma unroll
;                 for (int bj = 0; bj < 2; ++bj) { const u32x4 b = xr[m][bj];
;                     const f32x4 v0 = (f32x4){bf_lo(b.x), bf_hi(b.x), bf_lo(b.y), bf_hi(b.y)} + acc[ai][bj][m][0], v1 = (f32x4){bf_lo(b.z), bf_hi(b.z), bf_lo(b.w), bf_hi(b.w)} + acc[ai][bj][m][1];
;                     u32x4 w; w.x = cvt_pk_bf16(v0[0], v0[1]); w.y = cvt_pk_bf16(v0[2], v0[3]); w.z = cvt_pk_bf16(v1[0], v1[1]); w.w = cvt_pk_bf16(v1[2], v1[3]); *(u32x4*)(xb + off + bj * HALF) = w;
;                     s += (v0[0] * v0[0] + v0[1] * v0[1]) + (v0[2] * v0[2] + v0[3] * v0[3]) + (v1[0] * v1[0] + v1[1] * v1[1]) + (v1[2] * v1[2] + v1[3] * v1[3]); }
	v_add_u32_e32 v197, 0x90000, v196
	v_lshlrev_b32_e32 v242, 16, v218
	v_and_b32_e32 v243, 0xffff0000, v218
	v_lshlrev_b32_e32 v244, 16, v219
	v_and_b32_e32 v245, 0xffff0000, v219
	v_lshlrev_b32_e32 v246, 16, v220
	v_and_b32_e32 v247, 0xffff0000, v220
	v_lshlrev_b32_e32 v198, 16, v221
	v_and_b32_e32 v199, 0xffff0000, v221
	v_pk_add_f32 v[46:47], v[46:47], v[244:245]
	v_pk_add_f32 v[44:45], v[44:45], v[242:243]
	v_pk_add_f32 v[40:41], v[40:41], v[246:247]
	v_pk_add_f32 v[42:43], v[42:43], v[198:199]
	v_cvt_pk_bf16_f32 v242, v44, v45
	v_cvt_pk_bf16_f32 v243, v46, v47
	v_cvt_pk_bf16_f32 v244, v40, v41
	v_cvt_pk_bf16_f32 v245, v42, v43
	global_store_dwordx4 v197, v[242:245], s[64:65]
	v_mul_f32_e32 v246, v45, v45
	v_mul_f32_e32 v247, v47, v47
	v_fmac_f32_e32 v246, v44, v44
	v_fmac_f32_e32 v247, v46, v46
	v_add_f32_e32 v246, v246, v247
	v_mul_f32_e32 v247, v41, v41
	v_fmac_f32_e32 v247, v40, v40
	v_add_f32_e32 v246, v247, v246
	v_mul_f32_e32 v247, v43, v43
	v_fmac_f32_e32 v247, v42, v42
	v_add_f32_e32 v218, v247, v246
	v_lshlrev_b32_e32 v242, 16, v222
	v_and_b32_e32 v243, 0xffff0000, v222
	v_lshlrev_b32_e32 v244, 16, v223
	v_and_b32_e32 v245, 0xffff0000, v223
	v_lshlrev_b32_e32 v246, 16, v224
	v_and_b32_e32 v247, 0xffff0000, v224
	v_lshlrev_b32_e32 v198, 16, v225
	v_and_b32_e32 v199, 0xffff0000, v225
	v_pk_add_f32 v[38:39], v[38:39], v[244:245]
	v_pk_add_f32 v[36:37], v[36:37], v[242:243]
	v_pk_add_f32 v[32:33], v[32:33], v[246:247]
	v_pk_add_f32 v[34:35], v[34:35], v[198:199]
	v_cvt_pk_bf16_f32 v242, v36, v37
	v_cvt_pk_bf16_f32 v243, v38, v39
	v_cvt_pk_bf16_f32 v244, v32, v33
	v_cvt_pk_bf16_f32 v245, v34, v35
	global_store_dwordx4 v197, v[242:245], s[64:65] offset:256
	v_mul_f32_e32 v246, v37, v37
	v_mul_f32_e32 v247, v39, v39
	v_fmac_f32_e32 v246, v36, v36
	v_fmac_f32_e32 v247, v38, v38
	v_add_f32_e32 v246, v246, v247
	v_mul_f32_e32 v247, v33, v33
	v_fmac_f32_e32 v247, v32, v32
	v_add_f32_e32 v246, v247, v246
	v_mul_f32_e32 v247, v35, v35
	v_fmac_f32_e32 v247, v34, v34
	v_add_f32_e32 v246, v247, v246
	v_add_f32_e32 v218, v218, v246
	s_waitcnt vmcnt(14)
	v_add_u32_e32 v197, 0xa0000, v196
	v_lshlrev_b32_e32 v242, 16, v226
	v_and_b32_e32 v243, 0xffff0000, v226
	v_lshlrev_b32_e32 v244, 16, v227
	v_and_b32_e32 v245, 0xffff0000, v227
	v_lshlrev_b32_e32 v246, 16, v228
	v_and_b32_e32 v247, 0xffff0000, v228
	v_lshlrev_b32_e32 v198, 16, v229
	v_and_b32_e32 v199, 0xffff0000, v229
	v_pk_add_f32 v[30:31], v[30:31], v[244:245]
	v_pk_add_f32 v[28:29], v[28:29], v[242:243]
	v_pk_add_f32 v[24:25], v[24:25], v[246:247]
	v_pk_add_f32 v[26:27], v[26:27], v[198:199]
	v_cvt_pk_bf16_f32 v242, v28, v29
	v_cvt_pk_bf16_f32 v243, v30, v31
	v_cvt_pk_bf16_f32 v244, v24, v25
	v_cvt_pk_bf16_f32 v245, v26, v27
	global_store_dwordx4 v197, v[242:245], s[64:65]
	v_mul_f32_e32 v246, v29, v29
	v_mul_f32_e32 v247, v31, v31
	v_fmac_f32_e32 v246, v28, v28
	v_fmac_f32_e32 v247, v30, v30
	v_add_f32_e32 v246, v246, v247
	v_mul_f32_e32 v247, v25, v25
	v_fmac_f32_e32 v247, v24, v24
	v_add_f32_e32 v246, v247, v246
	v_mul_f32_e32 v247, v27, v27
	v_fmac_f32_e32 v247, v26, v26
	v_add_f32_e32 v226, v247, v246
	v_lshlrev_b32_e32 v242, 16, v230
	v_and_b32_e32 v243, 0xffff0000, v230
	v_lshlrev_b32_e32 v244, 16, v231
	v_and_b32_e32 v245, 0xffff0000, v231
	v_lshlrev_b32_e32 v246, 16, v232
	v_and_b32_e32 v247, 0xffff0000, v232
	v_lshlrev_b32_e32 v198, 16, v233
	v_and_b32_e32 v199, 0xffff0000, v233
	v_pk_add_f32 v[22:23], v[22:23], v[244:245]
	v_pk_add_f32 v[20:21], v[20:21], v[242:243]
	v_pk_add_f32 v[16:17], v[16:17], v[246:247]
	v_pk_add_f32 v[18:19], v[18:19], v[198:199]
	v_cvt_pk_bf16_f32 v242, v20, v21
	v_cvt_pk_bf16_f32 v243, v22, v23
	v_cvt_pk_bf16_f32 v244, v16, v17
	v_cvt_pk_bf16_f32 v245, v18, v19
	global_store_dwordx4 v197, v[242:245], s[64:65] offset:256
	v_mul_f32_e32 v246, v21, v21
	v_mul_f32_e32 v247, v23, v23
	v_fmac_f32_e32 v246, v20, v20
	v_fmac_f32_e32 v247, v22, v22
	v_add_f32_e32 v246, v246, v247
	v_mul_f32_e32 v247, v17, v17
	v_fmac_f32_e32 v247, v16, v16
	v_add_f32_e32 v246, v247, v246
	v_mul_f32_e32 v247, v19, v19
	v_fmac_f32_e32 v247, v18, v18
	v_add_f32_e32 v246, v247, v246
	v_add_f32_e32 v226, v226, v246
	s_waitcnt vmcnt(14)
; __device__ __forceinline__ unsigned cvt_pk_bf16(float lo, float hi) { unsigned r; asm volatile("v_cvt_pk_bf16_f32 %0, %1, %2" : "=v"(r) : "v"(lo), "v"(hi)); return r; }
; __device__ __forceinline__ float bf_lo(unsigned w) { return __uint_as_float(w << 16); }
; __device__ __forceinline__ float bf_hi(unsigned w) { return __uint_as_float(w & 0xffff0000u); }
;     __device__ __forceinline__ void operator()(const f32x4 (&acc)[2][2][4][2], const Unit& u, int wr, int wc, int fr, int fq) const {
;     ...
;                 for (int bj = 0; bj < 2; ++bj) { const u32x4 b = xr[m][bj];
;                     const f32x4 v0 = (f32x4){bf_lo(b.x), bf_hi(b.x), bf_lo(b.y), bf_hi(b.y)} + acc[ai][bj][m][0], v1 = (f32x4){bf_lo(b.z), bf_hi(b.z), bf_lo(b.w), bf_hi(b.w)} + acc[ai][bj][m][1];
;                     u32x4 w; w.x = cvt_pk_bf16(v0[0], v0[1]); w.y = cvt_pk_bf16(v0[2], v0[3]); w.z = cvt_pk_bf16(v1[0], v1[1]); w.w = cvt_pk_bf16(v1[2], v1[3]); *(u32x4*)(xb + off + bj * HALF) = w;
;                     s += (v0[0] * v0[0] + v0[1] * v0[1]) + (v0[2] * v0[2] + v0[3] * v0[3]) + (v1[0] * v1[0] + v1[1] * v1[1]) + (v1[2] * v1[2] + v1[3] * v1[3]); }
;                 s += __shfl_xor(s, 16); s += __shfl_xor(s, 32); if (fq == 0) part[((size_t)u.pm * 32 + u.pn * 4 + wc) * 256 + (row & 255)] = s; }
	v_add_u32_e32 v197, 0xb0000, v196
	v_lshlrev_b32_e32 v242, 16, v234
	v_and_b32_e32 v243, 0xffff0000, v234
	v_lshlrev_b32_e32 v244, 16, v235
	v_and_b32_e32 v245, 0xffff0000, v235
	v_lshlrev_b32_e32 v246, 16, v236
	v_and_b32_e32 v247, 0xffff0000, v236
	v_lshlrev_b32_e32 v198, 16, v237
	v_and_b32_e32 v199, 0xffff0000, v237
	v_pk_add_f32 v[14:15], v[14:15], v[244:245]
	v_pk_add_f32 v[12:13], v[12:13], v[242:243]
	v_pk_add_f32 v[8:9], v[8:9], v[246:247]
	v_pk_add_f32 v[10:11], v[10:11], v[198:199]
	v_cvt_pk_bf16_f32 v242, v12, v13
	v_cvt_pk_bf16_f32 v243, v14, v15
	v_cvt_pk_bf16_f32 v244, v8, v9
	v_cvt_pk_bf16_f32 v245, v10, v11
	global_store_dwordx4 v197, v[242:245], s[64:65]
	v_mul_f32_e32 v246, v13, v13
	v_mul_f32_e32 v247, v15, v15
	v_fmac_f32_e32 v246, v12, v12
	v_fmac_f32_e32 v247, v14, v14
	v_add_f32_e32 v246, v246, v247
	v_mul_f32_e32 v247, v9, v9
	v_fmac_f32_e32 v247, v8, v8
	v_add_f32_e32 v246, v247, v246
	v_mul_f32_e32 v247, v11, v11
	v_fmac_f32_e32 v247, v10, v10
	v_add_f32_e32 v234, v247, v246
	v_lshlrev_b32_e32 v242, 16, v238
	v_and_b32_e32 v243, 0xffff0000, v238
	v_lshlrev_b32_e32 v244, 16, v239
	v_and_b32_e32 v245, 0xffff0000, v239
	v_lshlrev_b32_e32 v246, 16, v240
	v_and_b32_e32 v247, 0xffff0000, v240
	v_lshlrev_b32_e32 v198, 16, v241
	v_and_b32_e32 v199, 0xffff0000, v241
	v_pk_add_f32 v[6:7], v[6:7], v[244:245]
	v_pk_add_f32 v[4:5], v[4:5], v[242:243]
	v_pk_add_f32 v[0:1], v[0:1], v[246:247]
	v_pk_add_f32 v[2:3], v[2:3], v[198:199]
	v_cvt_pk_bf16_f32 v242, v4, v5
	v_cvt_pk_bf16_f32 v243, v6, v7
	v_cvt_pk_bf16_f32 v244, v0, v1
	v_cvt_pk_bf16_f32 v245, v2, v3
	global_store_dwordx4 v197, v[242:245], s[64:65] offset:256
	v_mul_f32_e32 v246, v5, v5
	v_mul_f32_e32 v247, v7, v7
	v_fmac_f32_e32 v246, v4, v4
	v_fmac_f32_e32 v247, v6, v6
	v_add_f32_e32 v246, v246, v247
	v_mul_f32_e32 v247, v1, v1
	v_fmac_f32_e32 v247, v0, v0
	v_add_f32_e32 v246, v247, v246
	v_mul_f32_e32 v247, v3, v3
	v_fmac_f32_e32 v247, v2, v2
	v_add_f32_e32 v246, v247, v246
	v_add_f32_e32 v234, v234, v246
	ds_bpermute_b32 v129, v208, v128
	ds_bpermute_b32 v137, v208, v136
	ds_bpermute_b32 v145, v208, v144
	ds_bpermute_b32 v179, v208, v178
	ds_bpermute_b32 v187, v208, v186
	ds_bpermute_b32 v219, v208, v218
	ds_bpermute_b32 v227, v208, v226
	ds_bpermute_b32 v235, v208, v234
	v_add_u32_e32 v130, 0, v210
	v_add_u32_e32 v138, 16, v210
	v_add_u32_e32 v146, 32, v210
	v_add_u32_e32 v180, 48, v210
	v_add_u32_e32 v188, 128, v210
	v_add_u32_e32 v220, 144, v210
	v_add_u32_e32 v228, 160, v210
	v_add_u32_e32 v236, 176, v210
	s_waitcnt lgkmcnt(0)
	v_add_f32_e32 v128, v128, v129
	v_add_f32_e32 v136, v136, v137
	v_add_f32_e32 v144, v144, v145
	v_add_f32_e32 v178, v178, v179
	v_add_f32_e32 v186, v186, v187
	v_add_f32_e32 v218, v218, v219
	v_add_f32_e32 v226, v226, v227
	v_add_f32_e32 v234, v234, v235
	ds_bpermute_b32 v129, v209, v128
	ds_bpermute_b32 v137, v209, v136
	ds_bpermute_b32 v145, v209, v144
	ds_bpermute_b32 v179, v209, v178
	ds_bpermute_b32 v187, v209, v186
	ds_bpermute_b32 v219, v209, v218
	ds_bpermute_b32 v227, v209, v226
	ds_bpermute_b32 v235, v209, v234
	v_lshlrev_b32_e32 v130, 2, v130
	v_lshlrev_b32_e32 v138, 2, v138
	v_lshlrev_b32_e32 v146, 2, v146
	v_lshlrev_b32_e32 v180, 2, v180
	v_lshlrev_b32_e32 v188, 2, v188
	v_lshlrev_b32_e32 v220, 2, v220
	v_lshlrev_b32_e32 v228, 2, v228
	v_lshlrev_b32_e32 v236, 2, v236
	s_add_u32 s28, s54, s90
	s_addc_u32 s29, s55, s91
	s_waitcnt lgkmcnt(0)
	v_add_f32_e32 v128, v128, v129
	v_add_f32_e32 v136, v136, v137
	v_add_f32_e32 v144, v144, v145
	v_add_f32_e32 v178, v178, v179
	v_add_f32_e32 v186, v186, v187
	v_add_f32_e32 v218, v218, v219
	v_add_f32_e32 v226, v226, v227
	v_add_f32_e32 v234, v234, v235
	s_and_saveexec_b64 s[20:21], s[38:39]
	global_store_dword v130, v128, s[28:29]
	global_store_dword v138, v136, s[28:29]
	global_store_dword v146, v144, s[28:29]
	global_store_dword v180, v178, s[28:29]
	global_store_dword v188, v186, s[28:29]
	global_store_dword v220, v218, s[28:29]
	global_store_dword v228, v226, s[28:29]
	global_store_dword v236, v234, s[28:29]
